# pool unit: the 32 mixing-weight loads issued right after the first barrier (before the window-sum loop) instead of after the second barrier
# speedup vs baseline: 1.0052x; 1.0052x over previous
.LBB0_384:
	s_or_b64 exec, exec, s[4:5]
	v_lshl_add_u32 v4, v4, 9, v7
	s_waitcnt vmcnt(0)
	ds_write_b128 v4, v[0:3]
	v_bfe_u32 v0, v6, 6, 2
	v_ashrrev_i32_e32 v8, 3, v6
	v_lshlrev_b32_e64 v7, v0, 1
	v_and_b32_e32 v5, 0xffffffe0, v8
	v_sub_u32_e32 v1, v5, v7
	v_or_b32_e32 v9, v7, v5
	v_cmp_ge_i32_e32 vcc, v1, v9
	v_lshlrev_b32_sdwa v0, v216, v6 dst_sel:DWORD dst_unused:UNUSED_PAD src0_sel:DWORD src1_sel:BYTE_0
	v_lshrrev_b32_e32 v3, 5, v8
	v_lshlrev_b32_e32 v2, 9, v7
	s_waitcnt lgkmcnt(0)
	s_barrier
	s_load_dwordx2 s[98:99], s[16:17], 0x38
	v_readfirstlane_b32 s100, v6
	v_bfe_u32 v204, v6, 5, 1
	v_lshlrev_b32_e32 v205, 2, v32
	v_lshl_add_u32 v205, v204, 11, v205
	s_lshr_b32 s101, s100, 7
	s_lshl_b32 s101, s101, 14
	s_waitcnt lgkmcnt(0)
	s_add_u32 s98, s98, s24
	s_addc_u32 s99, s99, s25
	s_add_u32 s98, s98, s101
	s_addc_u32 s99, s99, 0
	s_lshr_b32 s101, s100, 1
	s_and_b32 s101, s101, 32
	s_lshl_b32 s101, s101, 2
	s_add_u32 s98, s98, s101
	s_addc_u32 s99, s99, 0
	global_load_dword v204, v205, s[98:99]
	global_load_dword v207, v205, s[98:99] offset:256
	global_load_dword v208, v205, s[98:99] offset:512
	global_load_dword v209, v205, s[98:99] offset:768
	global_load_dword v210, v205, s[98:99] offset:1024
	global_load_dword v211, v205, s[98:99] offset:1280
	global_load_dword v212, v205, s[98:99] offset:1536
	global_load_dword v213, v205, s[98:99] offset:1792
	v_add_u32_e32 v206, 0x1000, v205
	global_load_dword v214, v206, s[98:99]
	global_load_dword v215, v206, s[98:99] offset:256
	global_load_dword v220, v206, s[98:99] offset:512
	global_load_dword v221, v206, s[98:99] offset:768
	global_load_dword v222, v206, s[98:99] offset:1024
	global_load_dword v223, v206, s[98:99] offset:1280
	global_load_dword v224, v206, s[98:99] offset:1536
	global_load_dword v225, v206, s[98:99] offset:1792
	v_add_u32_e32 v206, 0x2000, v205
	global_load_dword v226, v206, s[98:99]
	global_load_dword v227, v206, s[98:99] offset:256
	global_load_dword v228, v206, s[98:99] offset:512
	global_load_dword v229, v206, s[98:99] offset:768
	global_load_dword v230, v206, s[98:99] offset:1024
	global_load_dword v231, v206, s[98:99] offset:1280
	global_load_dword v232, v206, s[98:99] offset:1536
	global_load_dword v233, v206, s[98:99] offset:1792
	v_add_u32_e32 v206, 0x3000, v205
	global_load_dword v234, v206, s[98:99]
	global_load_dword v235, v206, s[98:99] offset:256
	global_load_dword v236, v206, s[98:99] offset:512
	global_load_dword v237, v206, s[98:99] offset:768
	global_load_dword v238, v206, s[98:99] offset:1024
	global_load_dword v239, v206, s[98:99] offset:1280
	global_load_dword v240, v206, s[98:99] offset:1536
	global_load_dword v241, v206, s[98:99] offset:1792
	s_and_saveexec_b64 s[4:5], vcc
	s_xor_b64 s[4:5], exec, s[4:5]
	v_lshrrev_b32_e32 v3, 5, v8
	v_lshlrev_b32_sdwa v0, v216, v6 dst_sel:DWORD dst_unused:UNUSED_PAD src0_sel:DWORD src1_sel:BYTE_0
	v_lshlrev_b32_e32 v4, 14, v3
	v_lshlrev_b32_e32 v2, 9, v7
	s_or_saveexec_b64 s[4:5], s[4:5]
	v_mov_b32_e32 v8, 0
	s_xor_b64 exec, exec, s[4:5]
	s_cbranch_execz .LBB0_390
	v_lshlrev_b32_e32 v4, 14, v3
	v_or_b32_e32 v8, v4, v0
	v_sub_u32_e32 v8, v8, v2
	s_add_i32 s2, 0, 0x1000
	v_add_u32_e32 v10, s2, v8
	v_mov_b32_e32 v8, 0
	s_mov_b64 s[6:7], 0

.LBB0_391:
	v_add_u32_e32 v9, s2, v7
	v_add_u32_e32 v10, s2, v5
	v_add_u32_e32 v15, 0xffff4000, v9
	v_add_u32_e32 v16, 0xffff4000, v10
	v_add_u32_e32 v9, 0xffff4001, v9
	v_add_u32_e32 v10, 0xffff4001, v10
	v_max_i32_e32 v15, 0, v15
	v_min_i32_e32 v16, s1, v16
	v_max_i32_e32 v9, 0, v9
	v_min_i32_e32 v10, s1, v10
	v_sub_u32_e32 v15, v16, v15
	v_sub_u32_e32 v9, v10, v9
	v_cvt_f32_i32_e32 v10, v15
	v_add_u32_e32 v11, v4, v0
	ds_read_u16 v17, v11
	v_add_u32_e32 v12, v3, v0
	v_div_scale_f32 v16, s[4:5], v10, v10, v8
	v_rcp_f32_e32 v18, v16
	s_waitcnt lgkmcnt(0)
	v_lshlrev_b32_e32 v15, 16, v17
	v_div_scale_f32 v17, vcc, v8, v10, v8
	v_fma_f32 v19, -v16, v18, 1.0
	v_fmac_f32_e32 v18, v19, v18
	v_mul_f32_e32 v19, v17, v18
	v_fma_f32 v20, -v16, v19, v17
	v_fmac_f32_e32 v19, v20, v18
	v_fma_f32 v16, -v16, v19, v17
	v_div_fmas_f32 v16, v16, v18, v19
	v_div_fixup_f32 v10, v16, v10, v8
	v_sub_f32_e32 v10, v10, v15
	v_cvt_pk_bf16_f32 v10, v10, s0
	v_add_u32_e32 v14, v1, v0
	ds_write_b16 v12, v10
	v_add_u32_e32 v13, v2, v0
	ds_read_u16 v10, v14
	ds_read_u16 v15, v13
	ds_read_u16 v11, v11 offset:512
	v_cvt_f32_i32_e32 v9, v9
	s_add_i32 s2, s2, 2
	s_waitcnt lgkmcnt(2)
	v_lshlrev_b32_e32 v10, 16, v10
	s_waitcnt lgkmcnt(1)
	v_lshlrev_b32_e32 v15, 16, v15
	v_sub_f32_e32 v10, v15, v10
	v_add_f32_e32 v8, v8, v10
	v_div_scale_f32 v10, s[4:5], v9, v9, v8
	v_rcp_f32_e32 v15, v10
	v_div_scale_f32 v16, vcc, v8, v9, v8
	s_waitcnt lgkmcnt(0)
	v_lshlrev_b32_e32 v11, 16, v11
	v_fma_f32 v17, -v10, v15, 1.0
	v_fmac_f32_e32 v15, v17, v15
	v_mul_f32_e32 v17, v16, v15
	v_fma_f32 v18, -v10, v17, v16
	v_fmac_f32_e32 v17, v18, v15
	v_fma_f32 v10, -v10, v17, v16
	v_div_fmas_f32 v10, v10, v15, v17
	v_div_fixup_f32 v9, v10, v9, v8
	v_sub_f32_e32 v9, v9, v11
	v_cvt_pk_bf16_f32 v9, v9, s0
	ds_write_b16 v12, v9 offset:528
	ds_read_u16 v9, v14 offset:512
	ds_read_u16 v10, v13 offset:512
	v_add_u32_e32 v1, 0x400, v1
	v_add_u32_e32 v2, 0x400, v2
	v_add_u32_e32 v3, 0x420, v3
	s_waitcnt lgkmcnt(1)
	v_lshlrev_b32_e32 v9, 16, v9
	s_waitcnt lgkmcnt(0)
	v_lshlrev_b32_e32 v10, 16, v10
	v_sub_f32_e32 v9, v10, v9
	v_add_u32_e32 v4, 0x400, v4
	s_cmp_lg_u32 s2, 32
	v_add_f32_e32 v8, v8, v9
	s_cbranch_scc1 .LBB0_391
	s_barrier
	s_load_dwordx4 s[4:7], s[16:17], 0x38
	v_readfirstlane_b32 s10, v6
	s_ashr_i32 s1, s10, 7
	v_bfe_u32 v58, v6, 5, 1
	v_lshlrev_b32_e32 v160, 2, v32
	s_waitcnt lgkmcnt(0)
	s_add_u32 s2, s4, s24
	s_addc_u32 s11, s5, s25
	s_lshl_b32 s4, s1, 12
	s_ashr_i32 s5, s4, 31
	s_lshl_b64 s[4:5], s[4:5], 2
	s_add_u32 s4, s2, s4
	s_addc_u32 s5, s11, s5
	s_lshr_b32 s2, s10, 1
	s_and_b32 s2, s2, 32
	s_lshl_b32 s11, s2, 2
	s_add_u32 s4, s4, s11
	s_addc_u32 s5, s5, 0
	v_lshl_add_u64 v[0:1], s[4:5], 0, v[160:161]
	v_lshlrev_b32_e32 v160, 11, v58
	v_lshl_add_u64 v[8:9], v[0:1], 0, v[160:161]
	s_waitcnt vmcnt(0)
	v_mov_b32_e32 v4, v204
	v_mov_b32_e32 v5, v207
	v_mov_b32_e32 v6, v208
	v_mov_b32_e32 v7, v209
	v_mov_b32_e32 v10, v210
	v_mov_b32_e32 v11, v211
	v_mov_b32_e32 v12, v212
	v_mov_b32_e32 v13, v213
	v_add_co_u32_e32 v0, vcc, s83, v8
	s_movk_i32 s4, 0x2000
	s_nop 0
	v_addc_co_u32_e32 v1, vcc, 0, v9, vcc
	v_add_co_u32_e32 v46, vcc, s4, v8
	s_and_b32 s4, s10, 0xffffff80
	s_nop 0
	v_addc_co_u32_e32 v47, vcc, 0, v9, vcc
	v_mov_b32_e32 v33, v214
	v_mov_b32_e32 v42, v215
	v_mov_b32_e32 v43, v220
	v_mov_b32_e32 v44, v221
	v_mov_b32_e32 v45, v222
	v_mov_b32_e32 v48, v223
	v_mov_b32_e32 v49, v224
	v_mov_b32_e32 v50, v225
	v_mul_u32_u24_e32 v0, 0x210, v32
	v_lshlrev_b32_e32 v1, 4, v58
	s_add_i32 s4, s4, 0
	v_add3_u32 v59, s4, v1, v0
	ds_read_b128 v[0:3], v59 offset:40960
	ds_read_b128 v[34:37], v59 offset:40992
	s_movk_i32 s4, 0x3000
	v_add_co_u32_e32 v54, vcc, s4, v8
	s_lshl_b32 s1, s1, 6
	s_nop 0
	v_addc_co_u32_e32 v55, vcc, 0, v9, vcc
	s_or_b32 s1, s1, s2
	v_mov_b32_e32 v56, s6
	v_mov_b32_e32 v57, s7
	s_lshl_b32 s0, s0, 17
	v_lshl_or_b32 v160, v58, 13, s0
	s_mov_b64 s[4:5], 0
	ds_read_b128 v[38:41], v59 offset:57888
	s_waitcnt vmcnt(14)
	v_cvt_pk_bf16_f32 v4, v4, v5
	s_waitcnt vmcnt(12)
	v_cvt_pk_bf16_f32 v5, v6, v7
	s_waitcnt vmcnt(10)
	v_cvt_pk_bf16_f32 v6, v10, v11
	s_waitcnt vmcnt(8)
	v_cvt_pk_bf16_f32 v7, v12, v13
	s_waitcnt vmcnt(6)
	v_cvt_pk_bf16_f32 v42, v33, v42
	s_waitcnt lgkmcnt(2)
	v_mfma_f32_32x32x16_bf16 v[16:31], v[0:3], v[4:7], 0
	ds_read_b128 v[0:3], v59 offset:57856
	v_mov_b32_e32 v60, v226
	v_mov_b32_e32 v61, v227
	v_mov_b32_e32 v62, v228
	v_mov_b32_e32 v63, v229
	v_mov_b32_e32 v64, v230
	v_mov_b32_e32 v65, v231
	v_mov_b32_e32 v66, v232
	v_mov_b32_e32 v67, v234
	v_mov_b32_e32 v33, v233
	s_waitcnt vmcnt(13)
	v_cvt_pk_bf16_f32 v43, v43, v44
	s_waitcnt vmcnt(11)
	v_cvt_pk_bf16_f32 v44, v45, v48
	s_waitcnt vmcnt(9)
	v_cvt_pk_bf16_f32 v45, v49, v50
	s_waitcnt lgkmcnt(0)
	v_mfma_f32_32x32x16_bf16 v[0:15], v[0:3], v[4:7], 0
	v_mfma_f32_32x32x16_bf16 v[16:31], v[34:37], v[42:45], v[16:31]
	ds_read_b128 v[34:37], v59 offset:41024
	ds_read_b128 v[46:49], v59 offset:41056
	ds_read_b128 v[50:53], v59 offset:57920
	v_mfma_f32_32x32x16_bf16 v[0:15], v[38:41], v[42:45], v[0:15]
	v_mov_b32_e32 v43, v235
	v_mov_b32_e32 v44, v236
	v_mov_b32_e32 v45, v237
	v_mov_b32_e32 v68, v238
	v_mov_b32_e32 v69, v239
	v_mov_b32_e32 v70, v240
	s_nop 0
	v_mov_b32_e32 v54, v241
	v_or_b32_e32 v42, s1, v32
	s_waitcnt vmcnt(14)
	v_cvt_pk_bf16_f32 v38, v60, v61
	s_waitcnt vmcnt(12)
	v_cvt_pk_bf16_f32 v39, v62, v63
	s_waitcnt vmcnt(10)
	v_cvt_pk_bf16_f32 v40, v64, v65
	s_waitcnt vmcnt(7)
	v_cvt_pk_bf16_f32 v41, v66, v33
	s_waitcnt lgkmcnt(2)
	s_nop 0
	v_mfma_f32_32x32x16_bf16 v[16:31], v[34:37], v[38:41], v[16:31]
	v_add_u32_e32 v36, s30, v42
	v_ashrrev_i32_e32 v37, 31, v36
	v_lshl_add_u64 v[36:37], v[36:37], 2, v[56:57]
	ds_read_b128 v[32:35], v59 offset:57952
	s_waitcnt lgkmcnt(1)
	v_mfma_f32_32x32x16_bf16 v[0:15], v[50:53], v[38:41], v[0:15]
	global_load_dword v50, v[36:37], off
	v_lshl_add_u64 v[40:41], s[8:9], 0, v[160:161]
	s_waitcnt vmcnt(7)
	v_cvt_pk_bf16_f32 v36, v67, v43
	v_ashrrev_i32_e32 v43, 31, v42
	s_waitcnt vmcnt(5)
	v_cvt_pk_bf16_f32 v37, v44, v45
	v_lshl_add_u64 v[40:41], v[42:43], 1, v[40:41]
	s_waitcnt vmcnt(3)
	v_cvt_pk_bf16_f32 v38, v68, v69
	v_add_co_u32_e32 v42, vcc, s83, v40
	s_waitcnt vmcnt(1)
	v_cvt_pk_bf16_f32 v39, v70, v54
	v_addc_co_u32_e32 v43, vcc, 0, v41, vcc
	s_nop 0
	v_mfma_f32_32x32x16_bf16 v[16:31], v[46:49], v[36:39], v[16:31]
	s_waitcnt lgkmcnt(0)
	v_mfma_f32_32x32x16_bf16 v[0:15], v[32:35], v[36:39], v[0:15]
	s_waitcnt vmcnt(0)
	s_nop 8
	v_mul_f32_e32 v16, v16, v50
	v_mul_f32_e32 v17, v17, v50
	v_mul_f32_e32 v18, v18, v50
	v_cvt_pk_bf16_f32 v16, v16, s0
	v_cvt_pk_bf16_f32 v17, v17, s0
	v_cvt_pk_bf16_f32 v18, v18, s0
	global_store_short v[40:41], v16, off offset:1024
	global_store_short v[40:41], v17, off offset:3072
	global_store_short v[42:43], v18, off offset:1024
	v_mul_f32_e32 v16, v19, v50
	v_cvt_pk_bf16_f32 v16, v16, s0
	global_store_short v[42:43], v16, off offset:3072
	v_mul_f32_e32 v16, v20, v50
	v_cvt_pk_bf16_f32 v18, v16, s0
	s_movk_i32 s0, 0x4000
	v_add_co_u32_e32 v16, vcc, s0, v40
	v_mul_f32_e32 v0, v0, v50
	s_nop 0
	v_addc_co_u32_e32 v17, vcc, 0, v41, vcc
	global_store_short v[16:17], v18, off offset:1024
	v_mul_f32_e32 v18, v21, v50
	v_cvt_pk_bf16_f32 v18, v18, s0
	global_store_short v[16:17], v18, off offset:3072
	v_mul_f32_e32 v16, v22, v50
	v_cvt_pk_bf16_f32 v18, v16, s0
	s_movk_i32 s0, 0x5000
	v_add_co_u32_e32 v16, vcc, s0, v40
	s_nop 1
	v_addc_co_u32_e32 v17, vcc, 0, v41, vcc
	global_store_short v[16:17], v18, off offset:1024
	v_mul_f32_e32 v18, v23, v50
	v_cvt_pk_bf16_f32 v18, v18, s0
	global_store_short v[16:17], v18, off offset:3072
	v_mul_f32_e32 v16, v24, v50
	v_cvt_pk_bf16_f32 v18, v16, s0
	s_mov_b32 s0, 0x8000
	v_add_co_u32_e32 v16, vcc, s0, v40
	s_nop 1
	v_addc_co_u32_e32 v17, vcc, 0, v41, vcc
	global_store_short v[16:17], v18, off offset:1024
	v_mul_f32_e32 v18, v25, v50
	v_cvt_pk_bf16_f32 v18, v18, s0
	global_store_short v[16:17], v18, off offset:3072
	v_mul_f32_e32 v16, v26, v50
	v_cvt_pk_bf16_f32 v18, v16, s0
	s_mov_b32 s0, 0x9000
	v_add_co_u32_e32 v16, vcc, s0, v40
	s_nop 1
	v_addc_co_u32_e32 v17, vcc, 0, v41, vcc
	global_store_short v[16:17], v18, off offset:1024
	v_mul_f32_e32 v18, v27, v50
	v_cvt_pk_bf16_f32 v18, v18, s0
	global_store_short v[16:17], v18, off offset:3072
	v_mul_f32_e32 v16, v28, v50
	v_cvt_pk_bf16_f32 v18, v16, s0
	v_add_co_u32_e32 v16, vcc, s65, v40
	s_nop 1
	v_addc_co_u32_e32 v17, vcc, 0, v41, vcc
	global_store_short v[16:17], v18, off offset:1024
	v_mul_f32_e32 v18, v29, v50
	v_cvt_pk_bf16_f32 v18, v18, s0
	global_store_short v[16:17], v18, off offset:3072
	v_mul_f32_e32 v16, v30, v50
	v_cvt_pk_bf16_f32 v18, v16, s0
	s_mov_b32 s0, 0xd000
	v_add_co_u32_e32 v16, vcc, s0, v40
	v_cvt_pk_bf16_f32 v0, v0, s0
	s_nop 0
	v_addc_co_u32_e32 v17, vcc, 0, v41, vcc
	global_store_short v[16:17], v18, off offset:1024
	v_mul_f32_e32 v18, v31, v50
	v_cvt_pk_bf16_f32 v18, v18, s0
	s_mov_b32 s0, 0x10000
	global_store_short v[16:17], v18, off offset:3072
	v_add_co_u32_e32 v16, vcc, s0, v40
	s_nop 1
	v_addc_co_u32_e32 v17, vcc, 0, v41, vcc
	global_store_short v[16:17], v0, off offset:1024
	v_mul_f32_e32 v0, v1, v50
	v_cvt_pk_bf16_f32 v0, v0, s0
	global_store_short v[16:17], v0, off offset:3072
	v_mul_f32_e32 v0, v2, v50
	v_cvt_pk_bf16_f32 v2, v0, s0
	s_mov_b32 s0, 0x11000
	v_add_co_u32_e32 v0, vcc, s0, v40
	s_nop 1
	v_addc_co_u32_e32 v1, vcc, 0, v41, vcc
	global_store_short v[0:1], v2, off offset:1024
	v_mul_f32_e32 v2, v3, v50
	v_cvt_pk_bf16_f32 v2, v2, s0
	global_store_short v[0:1], v2, off offset:3072
	v_mul_f32_e32 v0, v4, v50
	v_cvt_pk_bf16_f32 v2, v0, s0
	s_mov_b32 s0, 0x14000
	v_add_co_u32_e32 v0, vcc, s0, v40
	s_nop 1
	v_addc_co_u32_e32 v1, vcc, 0, v41, vcc
	global_store_short v[0:1], v2, off offset:1024
	v_mul_f32_e32 v2, v5, v50
	v_cvt_pk_bf16_f32 v2, v2, s0
	global_store_short v[0:1], v2, off offset:3072
	v_mul_f32_e32 v0, v6, v50
	v_cvt_pk_bf16_f32 v2, v0, s0
	s_mov_b32 s0, 0x15000
	v_add_co_u32_e32 v0, vcc, s0, v40
	s_nop 1
	v_addc_co_u32_e32 v1, vcc, 0, v41, vcc
	global_store_short v[0:1], v2, off offset:1024
	v_mul_f32_e32 v2, v7, v50
	v_cvt_pk_bf16_f32 v2, v2, s0
	global_store_short v[0:1], v2, off offset:3072
	v_mul_f32_e32 v0, v8, v50
	v_cvt_pk_bf16_f32 v2, v0, s0
	v_add_co_u32_e32 v0, vcc, s76, v40
	s_nop 1
	v_addc_co_u32_e32 v1, vcc, 0, v41, vcc
	global_store_short v[0:1], v2, off offset:1024
	v_mul_f32_e32 v2, v9, v50
	v_cvt_pk_bf16_f32 v2, v2, s0
	global_store_short v[0:1], v2, off offset:3072
	v_mul_f32_e32 v0, v10, v50
	v_cvt_pk_bf16_f32 v2, v0, s0
	s_mov_b32 s0, 0x19000
	v_add_co_u32_e32 v0, vcc, s0, v40
	s_nop 1
	v_addc_co_u32_e32 v1, vcc, 0, v41, vcc
	global_store_short v[0:1], v2, off offset:1024
	v_mul_f32_e32 v2, v11, v50
	v_cvt_pk_bf16_f32 v2, v2, s0
	global_store_short v[0:1], v2, off offset:3072
	v_mul_f32_e32 v0, v12, v50
	v_cvt_pk_bf16_f32 v2, v0, s0
	s_mov_b32 s0, 0x1c000
	v_add_co_u32_e32 v0, vcc, s0, v40
	s_nop 1
	v_addc_co_u32_e32 v1, vcc, 0, v41, vcc
	global_store_short v[0:1], v2, off offset:1024
	v_mul_f32_e32 v2, v13, v50
	v_cvt_pk_bf16_f32 v2, v2, s0
	global_store_short v[0:1], v2, off offset:3072
	v_mul_f32_e32 v0, v14, v50
	v_cvt_pk_bf16_f32 v2, v0, s0
	v_add_co_u32_e32 v0, vcc, 0x1d000, v40
	s_nop 1
	v_addc_co_u32_e32 v1, vcc, 0, v41, vcc
	global_store_short v[0:1], v2, off offset:1024
	v_mul_f32_e32 v2, v15, v50
	v_cvt_pk_bf16_f32 v2, v2, s0
	global_store_short v[0:1], v2, off offset:3072
	s_barrier
